# k58: k52 + nt only on the in-projection epilogue's f32 present-K/V output stores (never re-read by the kernel)
# speedup vs baseline: 1.0320x; 1.0320x over previous
; __host__ __device__ __forceinline__ size_t ux_off(int m, int ch) { return ((size_t)((ch >> 4) * UXROWS + (m >> 4)) * UXR + (m & 15)) * 16 + (ch & 15); }
; __device__ __forceinline__ unsigned pk2(float lo, float hi) { typedef __bf16 bf16x2_t_ __attribute__((ext_vector_type(2))); f32x2 v = {lo, hi}; return __builtin_bit_cast(unsigned, __builtin_convertvector(v, bf16x2_t_)); }
;     __device__ __forceinline__ void operator()(const f32x4 (&acc)[2][2][4][2], const pg8::Unit& u, int wr, int wc, int fr, int fq) const {
;     ...
;                 bf16_t* bdst; float* fdst = nullptr;
;                 if (type == 0) bdst = UX_;
;                 else if (type == 1) bdst = ZS_ + (size_t)row * 512;
;                 else if (type == 2) bdst = Q + (size_t)row * 512;
;                 else if (type == 5) bdst = ZA_ + (size_t)row * 512;
;                 else {
;                     if (row < PT) { bdst = (type == 3 ? KB_ : VB_) + (size_t)row * 512; fdst = (type == 3 ? kp : vp) + (size_t)row * 512; }
;                     else { const int s = row - PT, b = s >> 6, t = s & 63; bdst = (type == 3 ? KS_ : VS_) + (size_t)(b * SKV + PAST + t) * 512; fdst = (type == 3 ? ksm : vsm) + (size_t)s * 512; }
;                 }
; #pragma unroll
;                 for (int bj = 0; bj < 2; ++bj) {
;                     u32x4 w; w.x = pk2(v[bj][0], v[bj][1]); w.y = pk2(v[bj][2], v[bj][3]); w.z = pk2(v[bj][4], v[bj][5]); w.w = pk2(v[bj][6], v[bj][7]);
;                     *(u32x4*)(bdst + (type == 0 ? ux_off(row, cb0 + bj * 32) : (size_t)(cb0 + bj * 32))) = w;
;                     if (fdst) { *(f32x4*)(fdst + cb0 + bj * 32) = (f32x4){v[bj][0], v[bj][1], v[bj][2], v[bj][3]}; *(f32x4*)(fdst + cb0 + bj * 32 + 4) = (f32x4){v[bj][4], v[bj][5], v[bj][6], v[bj][7]}; }
;                 }
.LBB0_306:
	v_lshlrev_b32_e32 v190, 2, v152
	v_mov_b32_e32 v191, v153
	v_cmp_ne_u64_e64 s[10:11], 0, v[116:117]
	v_lshl_add_u64 v[114:115], v[116:117], 0, v[190:191]
	v_cvt_pk_bf16_f32 v120, v128, v129
	v_cvt_pk_bf16_f32 v121, v130, v131
	v_cvt_pk_bf16_f32 v122, v132, v133
	v_cvt_pk_bf16_f32 v123, v134, v135
	v_lshl_add_u64 v[116:117], v[118:119], 1, v[112:113]
	global_store_dwordx4 v[116:117], v[120:123], off
	s_and_saveexec_b64 s[8:9], s[10:11]
	s_cbranch_execz .LBB0_308
	global_store_dwordx4 v[114:115], v[128:131], off nt
	global_store_dwordx4 v[114:115], v[132:135], off offset:16 nt

; __host__ __device__ __forceinline__ size_t ux_off(int m, int ch) { return ((size_t)((ch >> 4) * UXROWS + (m >> 4)) * UXR + (m & 15)) * 16 + (ch & 15); }
; __device__ __forceinline__ unsigned pk2(float lo, float hi) { typedef __bf16 bf16x2_t_ __attribute__((ext_vector_type(2))); f32x2 v = {lo, hi}; return __builtin_bit_cast(unsigned, __builtin_convertvector(v, bf16x2_t_)); }
;     __device__ __forceinline__ void operator()(const f32x4 (&acc)[2][2][4][2], const pg8::Unit& u, int wr, int wc, int fr, int fq) const {
;     ...
;                     if (row < PT) { bdst = (type == 3 ? KB_ : VB_) + (size_t)row * 512; fdst = (type == 3 ? kp : vp) + (size_t)row * 512; }
;                     else { const int s = row - PT, b = s >> 6, t = s & 63; bdst = (type == 3 ? KS_ : VS_) + (size_t)(b * SKV + PAST + t) * 512; fdst = (type == 3 ? ksm : vsm) + (size_t)s * 512; }
;                 }
; #pragma unroll
;                 for (int bj = 0; bj < 2; ++bj) {
;                     u32x4 w; w.x = pk2(v[bj][0], v[bj][1]); w.y = pk2(v[bj][2], v[bj][3]); w.z = pk2(v[bj][4], v[bj][5]); w.w = pk2(v[bj][6], v[bj][7]);
;                     *(u32x4*)(bdst + (type == 0 ? ux_off(row, cb0 + bj * 32) : (size_t)(cb0 + bj * 32))) = w;
;                     if (fdst) { *(f32x4*)(fdst + cb0 + bj * 32) = (f32x4){v[bj][0], v[bj][1], v[bj][2], v[bj][3]}; *(f32x4*)(fdst + cb0 + bj * 32 + 4) = (f32x4){v[bj][4], v[bj][5], v[bj][6], v[bj][7]}; }
.LBB0_312:
	v_cvt_pk_bf16_f32 v118, v136, v137
	v_cvt_pk_bf16_f32 v119, v138, v139
	v_cvt_pk_bf16_f32 v120, v140, v141
	v_cvt_pk_bf16_f32 v121, v142, v143
	v_lshl_add_u64 v[112:113], v[116:117], 1, v[112:113]
	global_store_dwordx4 v[112:113], v[118:121], off
	s_and_saveexec_b64 s[12:13], s[10:11]
	s_cbranch_execz .LBB0_314
	global_store_dwordx4 v[114:115], v[136:139], off offset:128 nt
	global_store_dwordx4 v[114:115], v[140:143], off offset:144 nt

; __host__ __device__ __forceinline__ size_t ux_off(int m, int ch) { return ((size_t)((ch >> 4) * UXROWS + (m >> 4)) * UXR + (m & 15)) * 16 + (ch & 15); }
; __device__ __forceinline__ unsigned pk2(float lo, float hi) { typedef __bf16 bf16x2_t_ __attribute__((ext_vector_type(2))); f32x2 v = {lo, hi}; return __builtin_bit_cast(unsigned, __builtin_convertvector(v, bf16x2_t_)); }
;     __device__ __forceinline__ void operator()(const f32x4 (&acc)[2][2][4][2], const pg8::Unit& u, int wr, int wc, int fr, int fq) const {
;     ...
;                     if (row < PT) { bdst = (type == 3 ? KB_ : VB_) + (size_t)row * 512; fdst = (type == 3 ? kp : vp) + (size_t)row * 512; }
;                     else { const int s = row - PT, b = s >> 6, t = s & 63; bdst = (type == 3 ? KS_ : VS_) + (size_t)(b * SKV + PAST + t) * 512; fdst = (type == 3 ? ksm : vsm) + (size_t)s * 512; }
;                 }
; #pragma unroll
;                 for (int bj = 0; bj < 2; ++bj) {
;                     u32x4 w; w.x = pk2(v[bj][0], v[bj][1]); w.y = pk2(v[bj][2], v[bj][3]); w.z = pk2(v[bj][4], v[bj][5]); w.w = pk2(v[bj][6], v[bj][7]);
;                     *(u32x4*)(bdst + (type == 0 ? ux_off(row, cb0 + bj * 32) : (size_t)(cb0 + bj * 32))) = w;
;                     if (fdst) { *(f32x4*)(fdst + cb0 + bj * 32) = (f32x4){v[bj][0], v[bj][1], v[bj][2], v[bj][3]}; *(f32x4*)(fdst + cb0 + bj * 32 + 4) = (f32x4){v[bj][4], v[bj][5], v[bj][6], v[bj][7]}; }
.LBB0_339:
	v_mov_b32_e32 v191, v153
	v_cmp_ne_u64_e64 s[14:15], 0, v[100:101]
	v_lshl_add_u64 v[98:99], v[100:101], 0, v[190:191]
	v_cvt_pk_bf16_f32 v104, v112, v113
	v_cvt_pk_bf16_f32 v105, v114, v115
	v_cvt_pk_bf16_f32 v106, v116, v117
	v_cvt_pk_bf16_f32 v107, v118, v119
	v_lshl_add_u64 v[100:101], v[102:103], 1, v[96:97]
	global_store_dwordx4 v[100:101], v[104:107], off
	s_and_saveexec_b64 s[84:85], s[14:15]
	s_cbranch_execz .LBB0_341
	global_store_dwordx4 v[98:99], v[112:115], off nt
	global_store_dwordx4 v[98:99], v[116:119], off offset:16 nt

; __host__ __device__ __forceinline__ size_t ux_off(int m, int ch) { return ((size_t)((ch >> 4) * UXROWS + (m >> 4)) * UXR + (m & 15)) * 16 + (ch & 15); }
; __device__ __forceinline__ unsigned pk2(float lo, float hi) { typedef __bf16 bf16x2_t_ __attribute__((ext_vector_type(2))); f32x2 v = {lo, hi}; return __builtin_bit_cast(unsigned, __builtin_convertvector(v, bf16x2_t_)); }
;     __device__ __forceinline__ void operator()(const f32x4 (&acc)[2][2][4][2], const pg8::Unit& u, int wr, int wc, int fr, int fq) const {
;     ...
;                     if (row < PT) { bdst = (type == 3 ? KB_ : VB_) + (size_t)row * 512; fdst = (type == 3 ? kp : vp) + (size_t)row * 512; }
;                     else { const int s = row - PT, b = s >> 6, t = s & 63; bdst = (type == 3 ? KS_ : VS_) + (size_t)(b * SKV + PAST + t) * 512; fdst = (type == 3 ? ksm : vsm) + (size_t)s * 512; }
;                 }
; #pragma unroll
;                 for (int bj = 0; bj < 2; ++bj) {
;                     u32x4 w; w.x = pk2(v[bj][0], v[bj][1]); w.y = pk2(v[bj][2], v[bj][3]); w.z = pk2(v[bj][4], v[bj][5]); w.w = pk2(v[bj][6], v[bj][7]);
;                     *(u32x4*)(bdst + (type == 0 ? ux_off(row, cb0 + bj * 32) : (size_t)(cb0 + bj * 32))) = w;
;                     if (fdst) { *(f32x4*)(fdst + cb0 + bj * 32) = (f32x4){v[bj][0], v[bj][1], v[bj][2], v[bj][3]}; *(f32x4*)(fdst + cb0 + bj * 32 + 4) = (f32x4){v[bj][4], v[bj][5], v[bj][6], v[bj][7]}; }
.LBB0_345:
	v_cvt_pk_bf16_f32 v102, v120, v121
	v_cvt_pk_bf16_f32 v103, v122, v123
	v_cvt_pk_bf16_f32 v104, v124, v125
	v_cvt_pk_bf16_f32 v105, v126, v127
	v_lshl_add_u64 v[96:97], v[100:101], 1, v[96:97]
	global_store_dwordx4 v[96:97], v[102:105], off
	s_and_saveexec_b64 s[84:85], s[14:15]
	s_cbranch_execz .LBB0_347
	global_store_dwordx4 v[98:99], v[120:123], off offset:128 nt
	global_store_dwordx4 v[98:99], v[124:127], off offset:144 nt

; __host__ __device__ __forceinline__ size_t ux_off(int m, int ch) { return ((size_t)((ch >> 4) * UXROWS + (m >> 4)) * UXR + (m & 15)) * 16 + (ch & 15); }
; __device__ __forceinline__ unsigned pk2(float lo, float hi) { typedef __bf16 bf16x2_t_ __attribute__((ext_vector_type(2))); f32x2 v = {lo, hi}; return __builtin_bit_cast(unsigned, __builtin_convertvector(v, bf16x2_t_)); }
;     __device__ __forceinline__ void operator()(const f32x4 (&acc)[2][2][4][2], const pg8::Unit& u, int wr, int wc, int fr, int fq) const {
;     ...
;                     if (row < PT) { bdst = (type == 3 ? KB_ : VB_) + (size_t)row * 512; fdst = (type == 3 ? kp : vp) + (size_t)row * 512; }
;                     else { const int s = row - PT, b = s >> 6, t = s & 63; bdst = (type == 3 ? KS_ : VS_) + (size_t)(b * SKV + PAST + t) * 512; fdst = (type == 3 ? ksm : vsm) + (size_t)s * 512; }
;                 }
; #pragma unroll
;                 for (int bj = 0; bj < 2; ++bj) {
;                     u32x4 w; w.x = pk2(v[bj][0], v[bj][1]); w.y = pk2(v[bj][2], v[bj][3]); w.z = pk2(v[bj][4], v[bj][5]); w.w = pk2(v[bj][6], v[bj][7]);
;                     *(u32x4*)(bdst + (type == 0 ? ux_off(row, cb0 + bj * 32) : (size_t)(cb0 + bj * 32))) = w;
;                     if (fdst) { *(f32x4*)(fdst + cb0 + bj * 32) = (f32x4){v[bj][0], v[bj][1], v[bj][2], v[bj][3]}; *(f32x4*)(fdst + cb0 + bj * 32 + 4) = (f32x4){v[bj][4], v[bj][5], v[bj][6], v[bj][7]}; }
.LBB0_372:
	v_mov_b32_e32 v191, v153
	v_cmp_ne_u64_e64 s[14:15], 0, v[84:85]
	v_lshl_add_u64 v[82:83], v[84:85], 0, v[190:191]
	v_cvt_pk_bf16_f32 v88, v96, v97
	v_cvt_pk_bf16_f32 v89, v98, v99
	v_cvt_pk_bf16_f32 v90, v100, v101
	v_cvt_pk_bf16_f32 v91, v102, v103
	v_lshl_add_u64 v[84:85], v[86:87], 1, v[80:81]
	global_store_dwordx4 v[84:85], v[88:91], off
	s_and_saveexec_b64 s[84:85], s[14:15]
	s_cbranch_execz .LBB0_374
	global_store_dwordx4 v[82:83], v[96:99], off nt
	global_store_dwordx4 v[82:83], v[100:103], off offset:16 nt

; __host__ __device__ __forceinline__ size_t ux_off(int m, int ch) { return ((size_t)((ch >> 4) * UXROWS + (m >> 4)) * UXR + (m & 15)) * 16 + (ch & 15); }
; __device__ __forceinline__ unsigned pk2(float lo, float hi) { typedef __bf16 bf16x2_t_ __attribute__((ext_vector_type(2))); f32x2 v = {lo, hi}; return __builtin_bit_cast(unsigned, __builtin_convertvector(v, bf16x2_t_)); }
;     __device__ __forceinline__ void operator()(const f32x4 (&acc)[2][2][4][2], const pg8::Unit& u, int wr, int wc, int fr, int fq) const {
;     ...
;                     if (row < PT) { bdst = (type == 3 ? KB_ : VB_) + (size_t)row * 512; fdst = (type == 3 ? kp : vp) + (size_t)row * 512; }
;                     else { const int s = row - PT, b = s >> 6, t = s & 63; bdst = (type == 3 ? KS_ : VS_) + (size_t)(b * SKV + PAST + t) * 512; fdst = (type == 3 ? ksm : vsm) + (size_t)s * 512; }
;                 }
; #pragma unroll
;                 for (int bj = 0; bj < 2; ++bj) {
;                     u32x4 w; w.x = pk2(v[bj][0], v[bj][1]); w.y = pk2(v[bj][2], v[bj][3]); w.z = pk2(v[bj][4], v[bj][5]); w.w = pk2(v[bj][6], v[bj][7]);
;                     *(u32x4*)(bdst + (type == 0 ? ux_off(row, cb0 + bj * 32) : (size_t)(cb0 + bj * 32))) = w;
;                     if (fdst) { *(f32x4*)(fdst + cb0 + bj * 32) = (f32x4){v[bj][0], v[bj][1], v[bj][2], v[bj][3]}; *(f32x4*)(fdst + cb0 + bj * 32 + 4) = (f32x4){v[bj][4], v[bj][5], v[bj][6], v[bj][7]}; }
.LBB0_378:
	v_cvt_pk_bf16_f32 v86, v104, v105
	v_cvt_pk_bf16_f32 v87, v106, v107
	v_cvt_pk_bf16_f32 v88, v108, v109
	v_cvt_pk_bf16_f32 v89, v110, v111
	v_lshl_add_u64 v[80:81], v[84:85], 1, v[80:81]
	global_store_dwordx4 v[80:81], v[86:89], off
	s_and_saveexec_b64 s[84:85], s[14:15]
	s_cbranch_execz .LBB0_380
	global_store_dwordx4 v[82:83], v[104:107], off offset:128 nt
	global_store_dwordx4 v[82:83], v[108:111], off offset:144 nt

; __host__ __device__ __forceinline__ size_t ux_off(int m, int ch) { return ((size_t)((ch >> 4) * UXROWS + (m >> 4)) * UXR + (m & 15)) * 16 + (ch & 15); }
; __device__ __forceinline__ unsigned pk2(float lo, float hi) { typedef __bf16 bf16x2_t_ __attribute__((ext_vector_type(2))); f32x2 v = {lo, hi}; return __builtin_bit_cast(unsigned, __builtin_convertvector(v, bf16x2_t_)); }
;     __device__ __forceinline__ void operator()(const f32x4 (&acc)[2][2][4][2], const pg8::Unit& u, int wr, int wc, int fr, int fq) const {
;     ...
;                     if (row < PT) { bdst = (type == 3 ? KB_ : VB_) + (size_t)row * 512; fdst = (type == 3 ? kp : vp) + (size_t)row * 512; }
;                     else { const int s = row - PT, b = s >> 6, t = s & 63; bdst = (type == 3 ? KS_ : VS_) + (size_t)(b * SKV + PAST + t) * 512; fdst = (type == 3 ? ksm : vsm) + (size_t)s * 512; }
;                 }
; #pragma unroll
;                 for (int bj = 0; bj < 2; ++bj) {
;                     u32x4 w; w.x = pk2(v[bj][0], v[bj][1]); w.y = pk2(v[bj][2], v[bj][3]); w.z = pk2(v[bj][4], v[bj][5]); w.w = pk2(v[bj][6], v[bj][7]);
;                     *(u32x4*)(bdst + (type == 0 ? ux_off(row, cb0 + bj * 32) : (size_t)(cb0 + bj * 32))) = w;
;                     if (fdst) { *(f32x4*)(fdst + cb0 + bj * 32) = (f32x4){v[bj][0], v[bj][1], v[bj][2], v[bj][3]}; *(f32x4*)(fdst + cb0 + bj * 32 + 4) = (f32x4){v[bj][4], v[bj][5], v[bj][6], v[bj][7]}; }
.LBB0_405:
	v_mov_b32_e32 v191, v153
	v_cmp_ne_u64_e64 s[14:15], 0, v[68:69]
	v_lshl_add_u64 v[66:67], v[68:69], 0, v[190:191]
	v_cvt_pk_bf16_f32 v72, v80, v81
	v_cvt_pk_bf16_f32 v73, v82, v83
	v_cvt_pk_bf16_f32 v74, v84, v85
	v_cvt_pk_bf16_f32 v75, v86, v87
	v_lshl_add_u64 v[68:69], v[70:71], 1, v[64:65]
	global_store_dwordx4 v[68:69], v[72:75], off
	s_and_saveexec_b64 s[84:85], s[14:15]
	s_cbranch_execz .LBB0_407
	global_store_dwordx4 v[66:67], v[80:83], off nt
	global_store_dwordx4 v[66:67], v[84:87], off offset:16 nt

; __host__ __device__ __forceinline__ size_t ux_off(int m, int ch) { return ((size_t)((ch >> 4) * UXROWS + (m >> 4)) * UXR + (m & 15)) * 16 + (ch & 15); }
; __device__ __forceinline__ unsigned pk2(float lo, float hi) { typedef __bf16 bf16x2_t_ __attribute__((ext_vector_type(2))); f32x2 v = {lo, hi}; return __builtin_bit_cast(unsigned, __builtin_convertvector(v, bf16x2_t_)); }
;     __device__ __forceinline__ void operator()(const f32x4 (&acc)[2][2][4][2], const pg8::Unit& u, int wr, int wc, int fr, int fq) const {
;     ...
;                     if (row < PT) { bdst = (type == 3 ? KB_ : VB_) + (size_t)row * 512; fdst = (type == 3 ? kp : vp) + (size_t)row * 512; }
;                     else { const int s = row - PT, b = s >> 6, t = s & 63; bdst = (type == 3 ? KS_ : VS_) + (size_t)(b * SKV + PAST + t) * 512; fdst = (type == 3 ? ksm : vsm) + (size_t)s * 512; }
;                 }
; #pragma unroll
;                 for (int bj = 0; bj < 2; ++bj) {
;                     u32x4 w; w.x = pk2(v[bj][0], v[bj][1]); w.y = pk2(v[bj][2], v[bj][3]); w.z = pk2(v[bj][4], v[bj][5]); w.w = pk2(v[bj][6], v[bj][7]);
;                     *(u32x4*)(bdst + (type == 0 ? ux_off(row, cb0 + bj * 32) : (size_t)(cb0 + bj * 32))) = w;
;                     if (fdst) { *(f32x4*)(fdst + cb0 + bj * 32) = (f32x4){v[bj][0], v[bj][1], v[bj][2], v[bj][3]}; *(f32x4*)(fdst + cb0 + bj * 32 + 4) = (f32x4){v[bj][4], v[bj][5], v[bj][6], v[bj][7]}; }
.LBB0_411:
	v_cvt_pk_bf16_f32 v70, v88, v89
	v_cvt_pk_bf16_f32 v71, v90, v91
	v_cvt_pk_bf16_f32 v72, v92, v93
	v_cvt_pk_bf16_f32 v73, v94, v95
	v_lshl_add_u64 v[64:65], v[68:69], 1, v[64:65]
	global_store_dwordx4 v[64:65], v[70:73], off
	s_and_saveexec_b64 s[84:85], s[14:15]
	s_cbranch_execz .LBB0_413
	global_store_dwordx4 v[66:67], v[88:91], off offset:128 nt
	global_store_dwordx4 v[66:67], v[92:95], off offset:144 nt

; __host__ __device__ __forceinline__ size_t ux_off(int m, int ch) { return ((size_t)((ch >> 4) * UXROWS + (m >> 4)) * UXR + (m & 15)) * 16 + (ch & 15); }
; __device__ __forceinline__ unsigned pk2(float lo, float hi) { typedef __bf16 bf16x2_t_ __attribute__((ext_vector_type(2))); f32x2 v = {lo, hi}; return __builtin_bit_cast(unsigned, __builtin_convertvector(v, bf16x2_t_)); }
;     __device__ __forceinline__ void operator()(const f32x4 (&acc)[2][2][4][2], const pg8::Unit& u, int wr, int wc, int fr, int fq) const {
;     ...
;                     if (row < PT) { bdst = (type == 3 ? KB_ : VB_) + (size_t)row * 512; fdst = (type == 3 ? kp : vp) + (size_t)row * 512; }
;                     else { const int s = row - PT, b = s >> 6, t = s & 63; bdst = (type == 3 ? KS_ : VS_) + (size_t)(b * SKV + PAST + t) * 512; fdst = (type == 3 ? ksm : vsm) + (size_t)s * 512; }
;                 }
; #pragma unroll
;                 for (int bj = 0; bj < 2; ++bj) {
;                     u32x4 w; w.x = pk2(v[bj][0], v[bj][1]); w.y = pk2(v[bj][2], v[bj][3]); w.z = pk2(v[bj][4], v[bj][5]); w.w = pk2(v[bj][6], v[bj][7]);
;                     *(u32x4*)(bdst + (type == 0 ? ux_off(row, cb0 + bj * 32) : (size_t)(cb0 + bj * 32))) = w;
;                     if (fdst) { *(f32x4*)(fdst + cb0 + bj * 32) = (f32x4){v[bj][0], v[bj][1], v[bj][2], v[bj][3]}; *(f32x4*)(fdst + cb0 + bj * 32 + 4) = (f32x4){v[bj][4], v[bj][5], v[bj][6], v[bj][7]}; }
.LBB0_438:
	v_mov_b32_e32 v191, v153
	v_cmp_ne_u64_e64 s[14:15], 0, v[52:53]
	v_lshl_add_u64 v[50:51], v[52:53], 0, v[190:191]
	v_cvt_pk_bf16_f32 v56, v64, v65
	v_cvt_pk_bf16_f32 v57, v66, v67
	v_cvt_pk_bf16_f32 v58, v68, v69
	v_cvt_pk_bf16_f32 v59, v70, v71
	v_lshl_add_u64 v[52:53], v[54:55], 1, v[48:49]
	global_store_dwordx4 v[52:53], v[56:59], off
	s_and_saveexec_b64 s[84:85], s[14:15]
	s_cbranch_execz .LBB0_440
	global_store_dwordx4 v[50:51], v[64:67], off nt
	global_store_dwordx4 v[50:51], v[68:71], off offset:16 nt

; __host__ __device__ __forceinline__ size_t ux_off(int m, int ch) { return ((size_t)((ch >> 4) * UXROWS + (m >> 4)) * UXR + (m & 15)) * 16 + (ch & 15); }
; __device__ __forceinline__ unsigned pk2(float lo, float hi) { typedef __bf16 bf16x2_t_ __attribute__((ext_vector_type(2))); f32x2 v = {lo, hi}; return __builtin_bit_cast(unsigned, __builtin_convertvector(v, bf16x2_t_)); }
;     __device__ __forceinline__ void operator()(const f32x4 (&acc)[2][2][4][2], const pg8::Unit& u, int wr, int wc, int fr, int fq) const {
;     ...
;                     if (row < PT) { bdst = (type == 3 ? KB_ : VB_) + (size_t)row * 512; fdst = (type == 3 ? kp : vp) + (size_t)row * 512; }
;                     else { const int s = row - PT, b = s >> 6, t = s & 63; bdst = (type == 3 ? KS_ : VS_) + (size_t)(b * SKV + PAST + t) * 512; fdst = (type == 3 ? ksm : vsm) + (size_t)s * 512; }
;                 }
; #pragma unroll
;                 for (int bj = 0; bj < 2; ++bj) {
;                     u32x4 w; w.x = pk2(v[bj][0], v[bj][1]); w.y = pk2(v[bj][2], v[bj][3]); w.z = pk2(v[bj][4], v[bj][5]); w.w = pk2(v[bj][6], v[bj][7]);
;                     *(u32x4*)(bdst + (type == 0 ? ux_off(row, cb0 + bj * 32) : (size_t)(cb0 + bj * 32))) = w;
;                     if (fdst) { *(f32x4*)(fdst + cb0 + bj * 32) = (f32x4){v[bj][0], v[bj][1], v[bj][2], v[bj][3]}; *(f32x4*)(fdst + cb0 + bj * 32 + 4) = (f32x4){v[bj][4], v[bj][5], v[bj][6], v[bj][7]}; }
.LBB0_444:
	v_cvt_pk_bf16_f32 v54, v72, v73
	v_cvt_pk_bf16_f32 v55, v74, v75
	v_cvt_pk_bf16_f32 v56, v76, v77
	v_cvt_pk_bf16_f32 v57, v78, v79
	v_lshl_add_u64 v[48:49], v[52:53], 1, v[48:49]
	global_store_dwordx4 v[48:49], v[54:57], off
	s_and_saveexec_b64 s[84:85], s[14:15]
	s_cbranch_execz .LBB0_446
	global_store_dwordx4 v[50:51], v[72:75], off offset:128 nt
	global_store_dwordx4 v[50:51], v[76:79], off offset:144 nt

; __host__ __device__ __forceinline__ size_t ux_off(int m, int ch) { return ((size_t)((ch >> 4) * UXROWS + (m >> 4)) * UXR + (m & 15)) * 16 + (ch & 15); }
; __device__ __forceinline__ unsigned pk2(float lo, float hi) { typedef __bf16 bf16x2_t_ __attribute__((ext_vector_type(2))); f32x2 v = {lo, hi}; return __builtin_bit_cast(unsigned, __builtin_convertvector(v, bf16x2_t_)); }
;     __device__ __forceinline__ void operator()(const f32x4 (&acc)[2][2][4][2], const pg8::Unit& u, int wr, int wc, int fr, int fq) const {
;     ...
;                     if (row < PT) { bdst = (type == 3 ? KB_ : VB_) + (size_t)row * 512; fdst = (type == 3 ? kp : vp) + (size_t)row * 512; }
;                     else { const int s = row - PT, b = s >> 6, t = s & 63; bdst = (type == 3 ? KS_ : VS_) + (size_t)(b * SKV + PAST + t) * 512; fdst = (type == 3 ? ksm : vsm) + (size_t)s * 512; }
;                 }
; #pragma unroll
;                 for (int bj = 0; bj < 2; ++bj) {
;                     u32x4 w; w.x = pk2(v[bj][0], v[bj][1]); w.y = pk2(v[bj][2], v[bj][3]); w.z = pk2(v[bj][4], v[bj][5]); w.w = pk2(v[bj][6], v[bj][7]);
;                     *(u32x4*)(bdst + (type == 0 ? ux_off(row, cb0 + bj * 32) : (size_t)(cb0 + bj * 32))) = w;
;                     if (fdst) { *(f32x4*)(fdst + cb0 + bj * 32) = (f32x4){v[bj][0], v[bj][1], v[bj][2], v[bj][3]}; *(f32x4*)(fdst + cb0 + bj * 32 + 4) = (f32x4){v[bj][4], v[bj][5], v[bj][6], v[bj][7]}; }
.LBB0_471:
	v_mov_b32_e32 v191, v153
	v_cmp_ne_u64_e64 s[14:15], 0, v[36:37]
	v_lshl_add_u64 v[34:35], v[36:37], 0, v[190:191]
	v_cvt_pk_bf16_f32 v40, v48, v49
	v_cvt_pk_bf16_f32 v41, v50, v51
	v_cvt_pk_bf16_f32 v42, v52, v53
	v_cvt_pk_bf16_f32 v43, v54, v55
	v_lshl_add_u64 v[36:37], v[38:39], 1, v[32:33]
	global_store_dwordx4 v[36:37], v[40:43], off
	s_and_saveexec_b64 s[84:85], s[14:15]
	s_cbranch_execz .LBB0_473
	global_store_dwordx4 v[34:35], v[48:51], off nt
	global_store_dwordx4 v[34:35], v[52:55], off offset:16 nt

; __host__ __device__ __forceinline__ size_t ux_off(int m, int ch) { return ((size_t)((ch >> 4) * UXROWS + (m >> 4)) * UXR + (m & 15)) * 16 + (ch & 15); }
; __device__ __forceinline__ unsigned pk2(float lo, float hi) { typedef __bf16 bf16x2_t_ __attribute__((ext_vector_type(2))); f32x2 v = {lo, hi}; return __builtin_bit_cast(unsigned, __builtin_convertvector(v, bf16x2_t_)); }
;     __device__ __forceinline__ void operator()(const f32x4 (&acc)[2][2][4][2], const pg8::Unit& u, int wr, int wc, int fr, int fq) const {
;     ...
;                     if (row < PT) { bdst = (type == 3 ? KB_ : VB_) + (size_t)row * 512; fdst = (type == 3 ? kp : vp) + (size_t)row * 512; }
;                     else { const int s = row - PT, b = s >> 6, t = s & 63; bdst = (type == 3 ? KS_ : VS_) + (size_t)(b * SKV + PAST + t) * 512; fdst = (type == 3 ? ksm : vsm) + (size_t)s * 512; }
;                 }
; #pragma unroll
;                 for (int bj = 0; bj < 2; ++bj) {
;                     u32x4 w; w.x = pk2(v[bj][0], v[bj][1]); w.y = pk2(v[bj][2], v[bj][3]); w.z = pk2(v[bj][4], v[bj][5]); w.w = pk2(v[bj][6], v[bj][7]);
;                     *(u32x4*)(bdst + (type == 0 ? ux_off(row, cb0 + bj * 32) : (size_t)(cb0 + bj * 32))) = w;
;                     if (fdst) { *(f32x4*)(fdst + cb0 + bj * 32) = (f32x4){v[bj][0], v[bj][1], v[bj][2], v[bj][3]}; *(f32x4*)(fdst + cb0 + bj * 32 + 4) = (f32x4){v[bj][4], v[bj][5], v[bj][6], v[bj][7]}; }
.LBB0_477:
	v_cvt_pk_bf16_f32 v38, v56, v57
	v_cvt_pk_bf16_f32 v39, v58, v59
	v_cvt_pk_bf16_f32 v40, v60, v61
	v_cvt_pk_bf16_f32 v41, v62, v63
	v_lshl_add_u64 v[32:33], v[36:37], 1, v[32:33]
	global_store_dwordx4 v[32:33], v[38:41], off
	s_and_saveexec_b64 s[84:85], s[14:15]
	s_cbranch_execz .LBB0_479
	global_store_dwordx4 v[34:35], v[56:59], off offset:128 nt
	global_store_dwordx4 v[34:35], v[60:63], off offset:144 nt

; __host__ __device__ __forceinline__ size_t ux_off(int m, int ch) { return ((size_t)((ch >> 4) * UXROWS + (m >> 4)) * UXR + (m & 15)) * 16 + (ch & 15); }
; __device__ __forceinline__ unsigned pk2(float lo, float hi) { typedef __bf16 bf16x2_t_ __attribute__((ext_vector_type(2))); f32x2 v = {lo, hi}; return __builtin_bit_cast(unsigned, __builtin_convertvector(v, bf16x2_t_)); }
;     __device__ __forceinline__ void operator()(const f32x4 (&acc)[2][2][4][2], const pg8::Unit& u, int wr, int wc, int fr, int fq) const {
;     ...
;                     if (row < PT) { bdst = (type == 3 ? KB_ : VB_) + (size_t)row * 512; fdst = (type == 3 ? kp : vp) + (size_t)row * 512; }
;                     else { const int s = row - PT, b = s >> 6, t = s & 63; bdst = (type == 3 ? KS_ : VS_) + (size_t)(b * SKV + PAST + t) * 512; fdst = (type == 3 ? ksm : vsm) + (size_t)s * 512; }
;                 }
; #pragma unroll
;                 for (int bj = 0; bj < 2; ++bj) {
;                     u32x4 w; w.x = pk2(v[bj][0], v[bj][1]); w.y = pk2(v[bj][2], v[bj][3]); w.z = pk2(v[bj][4], v[bj][5]); w.w = pk2(v[bj][6], v[bj][7]);
;                     *(u32x4*)(bdst + (type == 0 ? ux_off(row, cb0 + bj * 32) : (size_t)(cb0 + bj * 32))) = w;
;                     if (fdst) { *(f32x4*)(fdst + cb0 + bj * 32) = (f32x4){v[bj][0], v[bj][1], v[bj][2], v[bj][3]}; *(f32x4*)(fdst + cb0 + bj * 32 + 4) = (f32x4){v[bj][4], v[bj][5], v[bj][6], v[bj][7]}; }
.LBB0_504:
	v_mov_b32_e32 v191, v153
	v_cmp_ne_u64_e64 s[14:15], 0, v[20:21]
	v_lshl_add_u64 v[18:19], v[20:21], 0, v[190:191]
	v_cvt_pk_bf16_f32 v24, v32, v33
	v_cvt_pk_bf16_f32 v25, v34, v35
	v_cvt_pk_bf16_f32 v26, v36, v37
	v_cvt_pk_bf16_f32 v27, v38, v39
	v_lshl_add_u64 v[20:21], v[22:23], 1, v[16:17]
	global_store_dwordx4 v[20:21], v[24:27], off
	s_and_saveexec_b64 s[84:85], s[14:15]
	s_cbranch_execz .LBB0_506
	global_store_dwordx4 v[18:19], v[32:35], off nt
	global_store_dwordx4 v[18:19], v[36:39], off offset:16 nt

; __host__ __device__ __forceinline__ size_t ux_off(int m, int ch) { return ((size_t)((ch >> 4) * UXROWS + (m >> 4)) * UXR + (m & 15)) * 16 + (ch & 15); }
; __device__ __forceinline__ unsigned pk2(float lo, float hi) { typedef __bf16 bf16x2_t_ __attribute__((ext_vector_type(2))); f32x2 v = {lo, hi}; return __builtin_bit_cast(unsigned, __builtin_convertvector(v, bf16x2_t_)); }
;     __device__ __forceinline__ void operator()(const f32x4 (&acc)[2][2][4][2], const pg8::Unit& u, int wr, int wc, int fr, int fq) const {
;     ...
;                     if (row < PT) { bdst = (type == 3 ? KB_ : VB_) + (size_t)row * 512; fdst = (type == 3 ? kp : vp) + (size_t)row * 512; }
;                     else { const int s = row - PT, b = s >> 6, t = s & 63; bdst = (type == 3 ? KS_ : VS_) + (size_t)(b * SKV + PAST + t) * 512; fdst = (type == 3 ? ksm : vsm) + (size_t)s * 512; }
;                 }
; #pragma unroll
;                 for (int bj = 0; bj < 2; ++bj) {
;                     u32x4 w; w.x = pk2(v[bj][0], v[bj][1]); w.y = pk2(v[bj][2], v[bj][3]); w.z = pk2(v[bj][4], v[bj][5]); w.w = pk2(v[bj][6], v[bj][7]);
;                     *(u32x4*)(bdst + (type == 0 ? ux_off(row, cb0 + bj * 32) : (size_t)(cb0 + bj * 32))) = w;
;                     if (fdst) { *(f32x4*)(fdst + cb0 + bj * 32) = (f32x4){v[bj][0], v[bj][1], v[bj][2], v[bj][3]}; *(f32x4*)(fdst + cb0 + bj * 32 + 4) = (f32x4){v[bj][4], v[bj][5], v[bj][6], v[bj][7]}; }
.LBB0_510:
	v_cvt_pk_bf16_f32 v22, v40, v41
	v_cvt_pk_bf16_f32 v23, v42, v43
	v_cvt_pk_bf16_f32 v24, v44, v45
	v_cvt_pk_bf16_f32 v25, v46, v47
	v_lshl_add_u64 v[16:17], v[20:21], 1, v[16:17]
	global_store_dwordx4 v[16:17], v[22:25], off
	s_and_saveexec_b64 s[84:85], s[14:15]
	s_cbranch_execz .LBB0_512
	global_store_dwordx4 v[18:19], v[40:43], off offset:128 nt
	global_store_dwordx4 v[18:19], v[44:47], off offset:144 nt

; __host__ __device__ __forceinline__ size_t ux_off(int m, int ch) { return ((size_t)((ch >> 4) * UXROWS + (m >> 4)) * UXR + (m & 15)) * 16 + (ch & 15); }
; __device__ __forceinline__ unsigned pk2(float lo, float hi) { typedef __bf16 bf16x2_t_ __attribute__((ext_vector_type(2))); f32x2 v = {lo, hi}; return __builtin_bit_cast(unsigned, __builtin_convertvector(v, bf16x2_t_)); }
;     __device__ __forceinline__ void operator()(const f32x4 (&acc)[2][2][4][2], const pg8::Unit& u, int wr, int wc, int fr, int fq) const {
;     ...
;                     if (row < PT) { bdst = (type == 3 ? KB_ : VB_) + (size_t)row * 512; fdst = (type == 3 ? kp : vp) + (size_t)row * 512; }
;                     else { const int s = row - PT, b = s >> 6, t = s & 63; bdst = (type == 3 ? KS_ : VS_) + (size_t)(b * SKV + PAST + t) * 512; fdst = (type == 3 ? ksm : vsm) + (size_t)s * 512; }
;                 }
; #pragma unroll
;                 for (int bj = 0; bj < 2; ++bj) {
;                     u32x4 w; w.x = pk2(v[bj][0], v[bj][1]); w.y = pk2(v[bj][2], v[bj][3]); w.z = pk2(v[bj][4], v[bj][5]); w.w = pk2(v[bj][6], v[bj][7]);
;                     *(u32x4*)(bdst + (type == 0 ? ux_off(row, cb0 + bj * 32) : (size_t)(cb0 + bj * 32))) = w;
;                     if (fdst) { *(f32x4*)(fdst + cb0 + bj * 32) = (f32x4){v[bj][0], v[bj][1], v[bj][2], v[bj][3]}; *(f32x4*)(fdst + cb0 + bj * 32 + 4) = (f32x4){v[bj][4], v[bj][5], v[bj][6], v[bj][7]}; }
;                 }
.LBB0_537:
	v_mov_b32_e32 v191, v153
	v_cmp_ne_u64_e64 s[4:5], 0, v[4:5]
	v_lshl_add_u64 v[2:3], v[4:5], 0, v[190:191]
	v_cvt_pk_bf16_f32 v8, v16, v17
	v_cvt_pk_bf16_f32 v9, v18, v19
	v_cvt_pk_bf16_f32 v10, v20, v21
	v_cvt_pk_bf16_f32 v11, v22, v23
	v_lshl_add_u64 v[4:5], v[6:7], 1, v[0:1]
	global_store_dwordx4 v[4:5], v[8:11], off
	s_and_saveexec_b64 s[0:1], s[4:5]
	s_cbranch_execz .LBB0_546
	global_store_dwordx4 v[2:3], v[16:19], off nt
	global_store_dwordx4 v[2:3], v[20:23], off offset:16 nt
	s_or_b64 exec, exec, s[0:1]
	s_and_b64 vcc, exec, s[8:9]
	s_mov_b64 s[0:1], -1
	s_cbranch_vccz .LBB0_547

; __host__ __device__ __forceinline__ size_t ux_off(int m, int ch) { return ((size_t)((ch >> 4) * UXROWS + (m >> 4)) * UXR + (m & 15)) * 16 + (ch & 15); }
; __device__ __forceinline__ unsigned pk2(float lo, float hi) { typedef __bf16 bf16x2_t_ __attribute__((ext_vector_type(2))); f32x2 v = {lo, hi}; return __builtin_bit_cast(unsigned, __builtin_convertvector(v, bf16x2_t_)); }
;     __device__ __forceinline__ void operator()(const f32x4 (&acc)[2][2][4][2], const pg8::Unit& u, int wr, int wc, int fr, int fq) const {
;     ...
;                     if (row < PT) { bdst = (type == 3 ? KB_ : VB_) + (size_t)row * 512; fdst = (type == 3 ? kp : vp) + (size_t)row * 512; }
;                     else { const int s = row - PT, b = s >> 6, t = s & 63; bdst = (type == 3 ? KS_ : VS_) + (size_t)(b * SKV + PAST + t) * 512; fdst = (type == 3 ? ksm : vsm) + (size_t)s * 512; }
;                 }
; #pragma unroll
;                 for (int bj = 0; bj < 2; ++bj) {
;                     u32x4 w; w.x = pk2(v[bj][0], v[bj][1]); w.y = pk2(v[bj][2], v[bj][3]); w.z = pk2(v[bj][4], v[bj][5]); w.w = pk2(v[bj][6], v[bj][7]);
;                     *(u32x4*)(bdst + (type == 0 ? ux_off(row, cb0 + bj * 32) : (size_t)(cb0 + bj * 32))) = w;
;                     if (fdst) { *(f32x4*)(fdst + cb0 + bj * 32) = (f32x4){v[bj][0], v[bj][1], v[bj][2], v[bj][3]}; *(f32x4*)(fdst + cb0 + bj * 32 + 4) = (f32x4){v[bj][4], v[bj][5], v[bj][6], v[bj][7]}; }
.LBB0_541:
	v_cvt_pk_bf16_f32 v4, v24, v25
	v_cvt_pk_bf16_f32 v5, v26, v27
	v_cvt_pk_bf16_f32 v6, v28, v29
	v_cvt_pk_bf16_f32 v7, v30, v31
	v_lshl_add_u64 v[0:1], v[128:129], 1, v[0:1]
	global_store_dwordx4 v[0:1], v[4:7], off
	s_and_saveexec_b64 s[0:1], s[4:5]
	s_cbranch_execz .LBB0_543
	global_store_dwordx4 v[2:3], v[24:27], off offset:128 nt
	global_store_dwordx4 v[2:3], v[28:31], off offset:144 nt
